# nt (non-temporal) hint on the P1 (QKV) and P4 (SwiGLU hidden) epilogue stores: large write-once streams no longer displace the re-read A operand in the last-level cache
# baseline (speedup 1.0000x reference)
; __device__ __forceinline__ unsigned cvt_pk_bf16(float lo, float hi) { unsigned r; asm volatile("v_cvt_pk_bf16_f32 %0, %1, %2" : "=v"(r) : "v"(lo), "v"(hi)); return r; }
;     __device__ __forceinline__ void operator()(const f32x4 (&acc)[2][2][4][2], const Unit& u, int wr, int wc, int fr, int fq, const float (&rsv)[8]) const {
;         const int row0 = u.pm * BM + wr * 64 + fr; const int col0 = u.pn * BM + wc * 32 + 8 * fq;
; #pragma unroll
;         for (int ai = 0; ai < 2; ++ai)
; #pragma unroll
;             for (int m = 0; m < 4; ++m) { bf16_t* rowp = O + (size_t)(row0 + ai * HALF + m * 16) * ldc + col0; const float sc = RSC ? rsv[4 * ai + m] : 1.f;
; #pragma unroll
;                 for (int bj = 0; bj < 2; ++bj) { const f32x4 v0 = acc[ai][bj][m][0] * sc, v1 = acc[ai][bj][m][1] * sc;
;                     u32x4 w; w.x = cvt_pk_bf16(v0[0], v0[1]); w.y = cvt_pk_bf16(v0[2], v0[3]); w.z = cvt_pk_bf16(v1[0], v1[1]); w.w = cvt_pk_bf16(v1[2], v1[3]);
;                     *(u32x4*)(rowp + bj * HALF) = w; } }
;     }
.LBB0_126:
	s_lshl_b32 s15, s6, 8
	v_or_b32_e32 v158, s15, v149
	v_ashrrev_i32_e32 v159, 31, v158
	v_mad_i64_i32 v[160:161], s[2:3], v156, s0, 0
	v_lshl_add_u64 v[160:161], v[160:161], 1, s[78:79]
	v_lshlrev_b64 v[158:159], 1, v[158:159]
	v_lshl_add_u64 v[160:161], v[160:161], 0, v[158:159]
	s_waitcnt vmcnt(0)
	v_pk_mul_f32 v[128:129], v[128:129], v[146:147] op_sel_hi:[1,0]
	v_pk_mul_f32 v[126:127], v[126:127], v[146:147] op_sel_hi:[1,0]
	v_pk_mul_f32 v[162:163], v[124:125], v[146:147] op_sel_hi:[1,0]
	v_pk_mul_f32 v[124:125], v[122:123], v[146:147] op_sel_hi:[1,0]
	v_cvt_pk_bf16_f32 v122, v126, v127
	v_cvt_pk_bf16_f32 v123, v128, v129
	v_pk_mul_f32 v[118:119], v[118:119], v[146:147] op_sel_hi:[1,0]
	v_cvt_pk_bf16_f32 v124, v124, v125
	v_cvt_pk_bf16_f32 v125, v162, v163
	global_store_dwordx4 v[160:161], v[122:125], off nt
	v_pk_mul_f32 v[120:121], v[120:121], v[146:147] op_sel_hi:[1,0]
	v_pk_mul_f32 v[114:115], v[114:115], v[150:151] op_sel_hi:[1,0]
	v_pk_mul_f32 v[122:123], v[112:113], v[146:147] op_sel_hi:[1,0]
	v_pk_mul_f32 v[112:113], v[110:111], v[146:147] op_sel_hi:[1,0]
	v_cvt_pk_bf16_f32 v110, v118, v119
	v_cvt_pk_bf16_f32 v111, v120, v121
	v_pk_mul_f32 v[102:103], v[102:103], v[150:151] op_sel_hi:[1,0]
	v_cvt_pk_bf16_f32 v112, v112, v113
	v_cvt_pk_bf16_f32 v113, v122, v123
	global_store_dwordx4 v[160:161], v[110:113], off offset:256 nt
	v_pk_mul_f32 v[104:105], v[104:105], v[150:151] op_sel_hi:[1,0]
	v_pk_mul_f32 v[98:99], v[98:99], v[148:149] op_sel_hi:[1,0]
	v_or_b32_e32 v110, 16, v156
	v_mad_i64_i32 v[110:111], s[2:3], v110, s0, 0
	v_lshl_add_u64 v[110:111], v[110:111], 1, s[78:79]
	v_lshl_add_u64 v[110:111], v[110:111], 0, v[158:159]
	v_pk_mul_f32 v[112:113], v[116:117], v[150:151] op_sel_hi:[1,0]
	v_pk_mul_f32 v[116:117], v[108:109], v[150:151] op_sel_hi:[1,0]
	v_pk_mul_f32 v[108:109], v[106:107], v[150:151] op_sel_hi:[1,0]
	v_cvt_pk_bf16_f32 v106, v114, v115
	v_cvt_pk_bf16_f32 v107, v112, v113
	v_pk_mul_f32 v[86:87], v[86:87], v[148:149] op_sel_hi:[1,0]
	v_cvt_pk_bf16_f32 v108, v108, v109
	v_cvt_pk_bf16_f32 v109, v116, v117
	global_store_dwordx4 v[110:111], v[106:109], off nt
	v_pk_mul_f32 v[88:89], v[88:89], v[148:149] op_sel_hi:[1,0]
	v_pk_mul_f32 v[82:83], v[82:83], v[152:153] op_sel_hi:[1,0]
	v_pk_mul_f32 v[106:107], v[96:97], v[150:151] op_sel_hi:[1,0]
	v_pk_mul_f32 v[96:97], v[94:95], v[150:151] op_sel_hi:[1,0]
	v_cvt_pk_bf16_f32 v94, v102, v103
	v_cvt_pk_bf16_f32 v95, v104, v105
	v_pk_mul_f32 v[70:71], v[70:71], v[152:153] op_sel_hi:[1,0]
	v_cvt_pk_bf16_f32 v96, v96, v97
	v_cvt_pk_bf16_f32 v97, v106, v107
	global_store_dwordx4 v[110:111], v[94:97], off offset:256 nt
	v_pk_mul_f32 v[72:73], v[72:73], v[152:153] op_sel_hi:[1,0]
	v_pk_mul_f32 v[64:65], v[64:65], v[144:145] op_sel_hi:[1,0]
	v_or_b32_e32 v94, 32, v156
	v_mad_i64_i32 v[94:95], s[2:3], v94, s0, 0
	v_lshl_add_u64 v[94:95], v[94:95], 1, s[78:79]
	v_lshl_add_u64 v[94:95], v[94:95], 0, v[158:159]
	v_pk_mul_f32 v[96:97], v[100:101], v[148:149] op_sel_hi:[1,0]
	v_pk_mul_f32 v[100:101], v[92:93], v[148:149] op_sel_hi:[1,0]
	v_pk_mul_f32 v[92:93], v[90:91], v[148:149] op_sel_hi:[1,0]
	v_cvt_pk_bf16_f32 v90, v98, v99
	v_cvt_pk_bf16_f32 v91, v96, v97
	v_pk_mul_f32 v[62:63], v[62:63], v[144:145] op_sel_hi:[1,0]
	v_cvt_pk_bf16_f32 v92, v92, v93
	v_cvt_pk_bf16_f32 v93, v100, v101
	global_store_dwordx4 v[94:95], v[90:93], off nt
	v_pk_mul_f32 v[54:55], v[54:55], v[144:145] op_sel_hi:[1,0]
	v_pk_mul_f32 v[56:57], v[56:57], v[144:145] op_sel_hi:[1,0]
	v_pk_mul_f32 v[90:91], v[80:81], v[148:149] op_sel_hi:[1,0]
	v_pk_mul_f32 v[80:81], v[78:79], v[148:149] op_sel_hi:[1,0]
	v_cvt_pk_bf16_f32 v78, v86, v87
	v_cvt_pk_bf16_f32 v79, v88, v89
	v_pk_mul_f32 v[50:51], v[50:51], v[144:145] op_sel:[0,1]
	v_cvt_pk_bf16_f32 v80, v80, v81
	v_cvt_pk_bf16_f32 v81, v90, v91
	global_store_dwordx4 v[94:95], v[78:81], off offset:256 nt
	v_pk_mul_f32 v[38:39], v[38:39], v[144:145] op_sel:[0,1]
	v_pk_mul_f32 v[40:41], v[40:41], v[144:145] op_sel:[0,1]
	v_or_b32_e32 v78, 48, v156
	v_mad_i64_i32 v[78:79], s[2:3], v78, s0, 0
	v_lshl_add_u64 v[78:79], v[78:79], 1, s[78:79]
	v_lshl_add_u64 v[78:79], v[78:79], 0, v[158:159]
	v_pk_mul_f32 v[80:81], v[84:85], v[152:153] op_sel_hi:[1,0]
	v_pk_mul_f32 v[84:85], v[76:77], v[152:153] op_sel_hi:[1,0]
	v_pk_mul_f32 v[76:77], v[74:75], v[152:153] op_sel_hi:[1,0]
	v_cvt_pk_bf16_f32 v74, v82, v83
	v_cvt_pk_bf16_f32 v75, v80, v81
; __device__ __forceinline__ unsigned cvt_pk_bf16(float lo, float hi) { unsigned r; asm volatile("v_cvt_pk_bf16_f32 %0, %1, %2" : "=v"(r) : "v"(lo), "v"(hi)); return r; }
;     __device__ __forceinline__ void operator()(const f32x4 (&acc)[2][2][4][2], const Unit& u, int wr, int wc, int fr, int fq, const float (&rsv)[8]) const {
;         const int row0 = u.pm * BM + wr * 64 + fr; const int col0 = u.pn * BM + wc * 32 + 8 * fq;
; #pragma unroll
;         for (int ai = 0; ai < 2; ++ai)
; #pragma unroll
;             for (int m = 0; m < 4; ++m) { bf16_t* rowp = O + (size_t)(row0 + ai * HALF + m * 16) * ldc + col0; const float sc = RSC ? rsv[4 * ai + m] : 1.f;
; #pragma unroll
;                 for (int bj = 0; bj < 2; ++bj) { const f32x4 v0 = acc[ai][bj][m][0] * sc, v1 = acc[ai][bj][m][1] * sc;
;                     u32x4 w; w.x = cvt_pk_bf16(v0[0], v0[1]); w.y = cvt_pk_bf16(v0[2], v0[3]); w.z = cvt_pk_bf16(v1[0], v1[1]); w.w = cvt_pk_bf16(v1[2], v1[3]);
;                     *(u32x4*)(rowp + bj * HALF) = w; } }
;     }
	v_pk_mul_f32 v[34:35], v[34:35], v[154:155] op_sel_hi:[1,0]
	v_cvt_pk_bf16_f32 v76, v76, v77
	v_cvt_pk_bf16_f32 v77, v84, v85
	global_store_dwordx4 v[78:79], v[74:77], off nt
	v_pk_mul_f32 v[22:23], v[22:23], v[154:155] op_sel_hi:[1,0]
	v_pk_mul_f32 v[24:25], v[24:25], v[154:155] op_sel_hi:[1,0]
	v_pk_mul_f32 v[74:75], v[68:69], v[152:153] op_sel_hi:[1,0]
	v_pk_mul_f32 v[68:69], v[66:67], v[152:153] op_sel_hi:[1,0]
	v_cvt_pk_bf16_f32 v66, v70, v71
	v_cvt_pk_bf16_f32 v67, v72, v73
	s_and_b64 vcc, exec, s[72:73]
	v_cvt_pk_bf16_f32 v68, v68, v69
	v_cvt_pk_bf16_f32 v69, v74, v75
	global_store_dwordx4 v[78:79], v[66:69], off offset:256 nt
	v_readlane_b32 s44, v255, 2
	s_nop 0
	v_add_u32_e32 v66, 0x80, v156
	v_mad_i64_i32 v[66:67], s[2:3], v66, s0, 0
	v_lshl_add_u64 v[66:67], v[66:67], 1, s[78:79]
	v_lshl_add_u64 v[66:67], v[66:67], 0, v[158:159]
	v_pk_mul_f32 v[68:69], v[60:61], v[144:145] op_sel_hi:[1,0]
	v_pk_mul_f32 v[60:61], v[58:59], v[144:145] op_sel_hi:[1,0]
	v_cvt_pk_bf16_f32 v58, v62, v63
	v_cvt_pk_bf16_f32 v59, v64, v65
	s_nop 0
	v_cvt_pk_bf16_f32 v60, v60, v61
	v_cvt_pk_bf16_f32 v61, v68, v69
	global_store_dwordx4 v[66:67], v[58:61], off nt
	s_nop 1
	v_pk_mul_f32 v[58:59], v[48:49], v[144:145] op_sel_hi:[1,0]
	v_pk_mul_f32 v[48:49], v[46:47], v[144:145] op_sel_hi:[1,0]
	v_cvt_pk_bf16_f32 v46, v54, v55
	v_cvt_pk_bf16_f32 v47, v56, v57
	s_nop 0
	v_cvt_pk_bf16_f32 v48, v48, v49
	v_cvt_pk_bf16_f32 v49, v58, v59
	global_store_dwordx4 v[66:67], v[46:49], off offset:256 nt
	s_nop 1
	v_add_u32_e32 v46, 0x90, v156
	v_mad_i64_i32 v[46:47], s[2:3], v46, s0, 0
	v_lshl_add_u64 v[46:47], v[46:47], 1, s[78:79]
	v_lshl_add_u64 v[46:47], v[46:47], 0, v[158:159]
	v_pk_mul_f32 v[48:49], v[52:53], v[144:145] op_sel:[0,1]
	v_pk_mul_f32 v[52:53], v[44:45], v[144:145] op_sel:[0,1]
	v_pk_mul_f32 v[44:45], v[42:43], v[144:145] op_sel:[0,1]
	v_cvt_pk_bf16_f32 v42, v50, v51
	v_cvt_pk_bf16_f32 v43, v48, v49
	s_nop 0
	v_cvt_pk_bf16_f32 v44, v44, v45
	v_cvt_pk_bf16_f32 v45, v52, v53
	global_store_dwordx4 v[46:47], v[42:45], off nt
	s_nop 1
	v_pk_mul_f32 v[42:43], v[32:33], v[144:145] op_sel:[0,1]
	v_pk_mul_f32 v[32:33], v[30:31], v[144:145] op_sel:[0,1]
	v_cvt_pk_bf16_f32 v30, v38, v39
	v_cvt_pk_bf16_f32 v31, v40, v41
	s_nop 0
	v_cvt_pk_bf16_f32 v32, v32, v33
	v_cvt_pk_bf16_f32 v33, v42, v43
	global_store_dwordx4 v[46:47], v[30:33], off offset:256 nt
	s_nop 1
	v_add_u32_e32 v30, 0xa0, v156
	v_mad_i64_i32 v[30:31], s[2:3], v30, s0, 0
	v_lshl_add_u64 v[30:31], v[30:31], 1, s[78:79]
	v_lshl_add_u64 v[30:31], v[30:31], 0, v[158:159]
	v_pk_mul_f32 v[32:33], v[36:37], v[154:155] op_sel_hi:[1,0]
	v_pk_mul_f32 v[36:37], v[28:29], v[154:155] op_sel_hi:[1,0]
	v_pk_mul_f32 v[28:29], v[26:27], v[154:155] op_sel_hi:[1,0]
	v_cvt_pk_bf16_f32 v26, v34, v35
	v_cvt_pk_bf16_f32 v27, v32, v33
	s_nop 0
	v_cvt_pk_bf16_f32 v28, v28, v29
	v_cvt_pk_bf16_f32 v29, v36, v37
	global_store_dwordx4 v[30:31], v[26:29], off nt
	s_nop 1
	v_pk_mul_f32 v[26:27], v[16:17], v[154:155] op_sel_hi:[1,0]
	v_pk_mul_f32 v[16:17], v[14:15], v[154:155] op_sel_hi:[1,0]
	v_cvt_pk_bf16_f32 v14, v22, v23
	v_cvt_pk_bf16_f32 v15, v24, v25
	s_nop 0
	v_cvt_pk_bf16_f32 v16, v16, v17
	v_cvt_pk_bf16_f32 v17, v26, v27
	global_store_dwordx4 v[30:31], v[14:17], off offset:256 nt
	s_nop 1
	v_add_u32_e32 v14, 0xb0, v156
	v_mad_i64_i32 v[14:15], s[2:3], v14, s0, 0
	v_lshl_add_u64 v[14:15], v[14:15], 1, s[78:79]
	v_mov_b32_e32 v16, v155
	v_lshl_add_u64 v[14:15], v[14:15], 0, v[158:159]
	v_pk_mul_f32 v[20:21], v[20:21], v[16:17] op_sel_hi:[1,0]
	v_pk_mul_f32 v[18:19], v[18:19], v[16:17] op_sel_hi:[1,0]
	v_pk_mul_f32 v[22:23], v[12:13], v[16:17] op_sel_hi:[1,0]
	v_pk_mul_f32 v[12:13], v[10:11], v[16:17] op_sel_hi:[1,0]
	v_cvt_pk_bf16_f32 v10, v18, v19
	v_cvt_pk_bf16_f32 v11, v20, v21
	v_pk_mul_f32 v[8:9], v[8:9], v[16:17] op_sel_hi:[1,0]
	v_cvt_pk_bf16_f32 v12, v12, v13
	v_cvt_pk_bf16_f32 v13, v22, v23
	global_store_dwordx4 v[14:15], v[10:13], off nt
	v_pk_mul_f32 v[6:7], v[6:7], v[16:17] op_sel_hi:[1,0]
	s_nop 0
	v_pk_mul_f32 v[10:11], v[4:5], v[16:17] op_sel_hi:[1,0]
	v_pk_mul_f32 v[4:5], v[2:3], v[16:17] op_sel_hi:[1,0]
	v_cvt_pk_bf16_f32 v2, v6, v7
	v_cvt_pk_bf16_f32 v3, v8, v9
	s_nop 0
	v_cvt_pk_bf16_f32 v4, v4, v5
	v_cvt_pk_bf16_f32 v5, v10, v11
	global_store_dwordx4 v[14:15], v[2:5], off offset:256 nt
	s_cbranch_vccz .LBB0_128
	s_cmp_eq_u32 s6, 4
	s_cselect_b64 s[8:9], -1, 0
	s_cbranch_execz .LBB0_129
	s_branch .LBB0_133

; __device__ __forceinline__ unsigned cvt_pk_bf16(float lo, float hi) { unsigned r; asm volatile("v_cvt_pk_bf16_f32 %0, %1, %2" : "=v"(r) : "v"(lo), "v"(hi)); return r; }
; __device__ __forceinline__ float silu_mul(float g, float u) { const float e = __builtin_amdgcn_exp2f(g * -1.4426950408889634f); return g * __builtin_amdgcn_rcpf(1.0f + e) * u; }
;     __device__ __forceinline__ void operator()(const f32x4 (&acc)[2][2][4][2], const Unit& u, int wr, int wc, int fr, int fq, const float (&rsv)[8]) const {
;         const int row0 = u.pm * BM + wr * 64 + fr; const int col0 = u.pn * HALF + wc * 32 + 8 * fq;
; #pragma unroll
;         for (int ai = 0; ai < 2; ++ai)
; #pragma unroll
;             for (int m = 0; m < 4; ++m) { bf16_t* rowp = O + (size_t)(row0 + ai * HALF + m * 16) * ldc + col0;
;                 const float sc = rsv[4 * ai + m];
;                 const f32x4 g0 = acc[ai][0][m][0] * sc, g1 = acc[ai][0][m][1] * sc, u0 = acc[ai][1][m][0] * sc, u1 = acc[ai][1][m][1] * sc;
;                 u32x4 w; w.x = cvt_pk_bf16(silu_mul(g0[0], u0[0]), silu_mul(g0[1], u0[1])); w.y = cvt_pk_bf16(silu_mul(g0[2], u0[2]), silu_mul(g0[3], u0[3]));
;                 w.z = cvt_pk_bf16(silu_mul(g1[0], u1[0]), silu_mul(g1[1], u1[1])); w.w = cvt_pk_bf16(silu_mul(g1[2], u1[2]), silu_mul(g1[3], u1[3]));
;                 *(u32x4*)rowp = w; }
.LBB0_733:
	s_waitcnt vmcnt(0)
	v_pk_mul_f32 v[126:127], v[126:127], v[146:147] op_sel_hi:[1,0]
	v_pk_mul_f32 v[164:165], v[116:117], v[146:147] op_sel_hi:[1,0]
	v_pk_mul_f32 v[116:117], v[114:115], v[146:147] op_sel_hi:[1,0]
	v_mul_f32_e32 v114, 0xbfb8aa3b, v126
	v_mul_f32_e32 v115, 0xbfb8aa3b, v127
	v_exp_f32_e32 v114, v114
	v_exp_f32_e32 v115, v115
	v_pk_mul_f32 v[118:119], v[118:119], v[146:147] op_sel_hi:[1,0]
	v_pk_mul_f32 v[128:129], v[128:129], v[146:147] op_sel_hi:[1,0]
	v_add_f32_e32 v114, 1.0, v114
	v_add_f32_e32 v115, 1.0, v115
	v_rcp_f32_e32 v114, v114
	v_rcp_f32_e32 v115, v115
	v_pk_mul_f32 v[120:121], v[120:121], v[146:147] op_sel_hi:[1,0]
	v_pk_mul_f32 v[122:123], v[122:123], v[146:147] op_sel_hi:[1,0]
	v_mul_f32_e32 v114, v126, v114
	v_mul_f32_e32 v115, v127, v115
	v_mul_f32_e32 v114, v118, v114
	v_mul_f32_e32 v115, v119, v115
	v_cvt_pk_bf16_f32 v114, v114, v115
	v_mul_f32_e32 v115, 0xbfb8aa3b, v128
	v_mul_f32_e32 v118, 0xbfb8aa3b, v129
	v_exp_f32_e32 v115, v115
	v_exp_f32_e32 v118, v118
	v_pk_mul_f32 v[124:125], v[124:125], v[146:147] op_sel_hi:[1,0]
	v_lshl_or_b32 v160, s2, 7, v147
	v_add_f32_e32 v115, 1.0, v115
	v_add_f32_e32 v118, 1.0, v118
	v_rcp_f32_e32 v115, v115
	v_rcp_f32_e32 v118, v118
	v_ashrrev_i32_e32 v161, 31, v160
	v_mov_b64_e32 v[158:159], s[10:11]
	v_mul_f32_e32 v115, v128, v115
	v_mul_f32_e32 v118, v129, v118
	v_mul_f32_e32 v115, v120, v115
	v_mul_f32_e32 v118, v121, v118
	v_cvt_pk_bf16_f32 v115, v115, v118
	v_mul_f32_e32 v118, 0xbfb8aa3b, v122
	v_exp_f32_e32 v118, v118
	s_movk_i32 s15, 0x1600
	v_mad_i64_i32 v[162:163], s[2:3], v156, s15, v[158:159]
	v_add_f32_e32 v118, 1.0, v118
	v_rcp_f32_e32 v118, v118
	v_lshlrev_b64 v[160:161], 1, v[160:161]
	v_lshl_add_u64 v[162:163], v[162:163], 0, v[160:161]
	v_pk_mul_f32 v[110:111], v[110:111], v[150:151] op_sel_hi:[1,0]
	v_mul_f32_e32 v118, v122, v118
	v_mul_f32_e32 v116, v116, v118
	v_mul_f32_e32 v118, 0xbfb8aa3b, v123
	v_exp_f32_e32 v118, v118
	v_pk_mul_f32 v[102:103], v[102:103], v[150:151] op_sel_hi:[1,0]
	v_pk_mul_f32 v[112:113], v[112:113], v[150:151] op_sel_hi:[1,0]
	v_pk_mul_f32 v[104:105], v[104:105], v[150:151] op_sel_hi:[1,0]
	v_add_f32_e32 v118, 1.0, v118
	v_rcp_f32_e32 v118, v118
	v_pk_mul_f32 v[106:107], v[106:107], v[150:151] op_sel_hi:[1,0]
	v_pk_mul_f32 v[108:109], v[108:109], v[150:151] op_sel_hi:[1,0]
	v_pk_mul_f32 v[94:95], v[94:95], v[148:149] op_sel_hi:[1,0]
	v_mul_f32_e32 v118, v123, v118
	v_mul_f32_e32 v117, v117, v118
	v_cvt_pk_bf16_f32 v116, v116, v117
	v_mul_f32_e32 v117, 0xbfb8aa3b, v124
	v_exp_f32_e32 v117, v117
	v_mul_f32_e32 v118, 0xbfb8aa3b, v125
	v_exp_f32_e32 v118, v118
	v_pk_mul_f32 v[86:87], v[86:87], v[148:149] op_sel_hi:[1,0]
	v_add_f32_e32 v117, 1.0, v117
	v_rcp_f32_e32 v117, v117
	v_add_f32_e32 v118, 1.0, v118
	v_rcp_f32_e32 v118, v118
	v_pk_mul_f32 v[96:97], v[96:97], v[148:149] op_sel_hi:[1,0]
	v_mul_f32_e32 v117, v124, v117
	v_mul_f32_e32 v117, v164, v117
	v_mul_f32_e32 v118, v125, v118
	v_mul_f32_e32 v118, v165, v118
	v_cvt_pk_bf16_f32 v117, v117, v118
	global_store_dwordx4 v[162:163], v[114:117], off nt
	v_pk_mul_f32 v[88:89], v[88:89], v[148:149] op_sel_hi:[1,0]
	v_pk_mul_f32 v[90:91], v[90:91], v[148:149] op_sel_hi:[1,0]
	v_pk_mul_f32 v[116:117], v[100:101], v[150:151] op_sel_hi:[1,0]
	v_pk_mul_f32 v[100:101], v[98:99], v[150:151] op_sel_hi:[1,0]
	v_mul_f32_e32 v98, 0xbfb8aa3b, v110
	v_mul_f32_e32 v99, 0xbfb8aa3b, v111
	v_exp_f32_e32 v98, v98
	v_exp_f32_e32 v99, v99
	v_or_b32_e32 v114, 16, v156
	v_mad_i64_i32 v[114:115], s[2:3], v114, s15, v[158:159]
	v_add_f32_e32 v98, 1.0, v98
	v_add_f32_e32 v99, 1.0, v99
	v_rcp_f32_e32 v98, v98
	v_rcp_f32_e32 v99, v99
	v_lshl_add_u64 v[114:115], v[114:115], 0, v[160:161]
	v_pk_mul_f32 v[92:93], v[92:93], v[148:149] op_sel_hi:[1,0]
	v_mul_f32_e32 v98, v110, v98
	v_mul_f32_e32 v99, v111, v99
	v_mul_f32_e32 v98, v102, v98
	v_mul_f32_e32 v99, v103, v99
	v_cvt_pk_bf16_f32 v98, v98, v99
	v_mul_f32_e32 v99, 0xbfb8aa3b, v112
	v_mul_f32_e32 v102, 0xbfb8aa3b, v113
	v_exp_f32_e32 v99, v99
	v_exp_f32_e32 v102, v102
	v_pk_mul_f32 v[78:79], v[78:79], v[152:153] op_sel_hi:[1,0]
	v_pk_mul_f32 v[70:71], v[70:71], v[152:153] op_sel_hi:[1,0]
	v_add_f32_e32 v99, 1.0, v99
	v_add_f32_e32 v102, 1.0, v102
	v_rcp_f32_e32 v99, v99
	v_rcp_f32_e32 v102, v102
	v_pk_mul_f32 v[80:81], v[80:81], v[152:153] op_sel_hi:[1,0]
	v_pk_mul_f32 v[72:73], v[72:73], v[152:153] op_sel_hi:[1,0]
	v_mul_f32_e32 v99, v112, v99
	v_mul_f32_e32 v102, v113, v102
	v_mul_f32_e32 v99, v104, v99
	v_mul_f32_e32 v102, v105, v102
	v_cvt_pk_bf16_f32 v99, v99, v102
	v_mul_f32_e32 v102, 0xbfb8aa3b, v106
	v_exp_f32_e32 v102, v102
	v_pk_mul_f32 v[74:75], v[74:75], v[152:153] op_sel_hi:[1,0]
	v_pk_mul_f32 v[76:77], v[76:77], v[152:153] op_sel_hi:[1,0]
	v_pk_mul_f32 v[62:63], v[62:63], v[144:145] op_sel_hi:[1,0]
	v_add_f32_e32 v102, 1.0, v102
	v_rcp_f32_e32 v102, v102
	v_pk_mul_f32 v[54:55], v[54:55], v[144:145] op_sel_hi:[1,0]
	v_pk_mul_f32 v[64:65], v[64:65], v[144:145] op_sel_hi:[1,0]
	v_pk_mul_f32 v[56:57], v[56:57], v[144:145] op_sel_hi:[1,0]
	v_mul_f32_e32 v102, v106, v102
	v_mul_f32_e32 v100, v100, v102
	v_mul_f32_e32 v102, 0xbfb8aa3b, v107
	v_exp_f32_e32 v102, v102
	v_pk_mul_f32 v[58:59], v[58:59], v[144:145] op_sel_hi:[1,0]
	v_pk_mul_f32 v[60:61], v[60:61], v[144:145] op_sel_hi:[1,0]
	v_pk_mul_f32 v[46:47], v[46:47], v[144:145] op_sel:[0,1]
	v_add_f32_e32 v102, 1.0, v102
	v_rcp_f32_e32 v102, v102
	v_pk_mul_f32 v[38:39], v[38:39], v[144:145] op_sel:[0,1]
	v_pk_mul_f32 v[48:49], v[48:49], v[144:145] op_sel:[0,1]
	v_pk_mul_f32 v[40:41], v[40:41], v[144:145] op_sel:[0,1]
	v_mul_f32_e32 v102, v107, v102
	v_mul_f32_e32 v101, v101, v102
; __device__ __forceinline__ unsigned cvt_pk_bf16(float lo, float hi) { unsigned r; asm volatile("v_cvt_pk_bf16_f32 %0, %1, %2" : "=v"(r) : "v"(lo), "v"(hi)); return r; }
; __device__ __forceinline__ float silu_mul(float g, float u) { const float e = __builtin_amdgcn_exp2f(g * -1.4426950408889634f); return g * __builtin_amdgcn_rcpf(1.0f + e) * u; }
;     __device__ __forceinline__ void operator()(const f32x4 (&acc)[2][2][4][2], const Unit& u, int wr, int wc, int fr, int fq, const float (&rsv)[8]) const {
;         const int row0 = u.pm * BM + wr * 64 + fr; const int col0 = u.pn * HALF + wc * 32 + 8 * fq;
; #pragma unroll
;         for (int ai = 0; ai < 2; ++ai)
; #pragma unroll
;             for (int m = 0; m < 4; ++m) { bf16_t* rowp = O + (size_t)(row0 + ai * HALF + m * 16) * ldc + col0;
;                 const float sc = rsv[4 * ai + m];
;                 const f32x4 g0 = acc[ai][0][m][0] * sc, g1 = acc[ai][0][m][1] * sc, u0 = acc[ai][1][m][0] * sc, u1 = acc[ai][1][m][1] * sc;
;                 u32x4 w; w.x = cvt_pk_bf16(silu_mul(g0[0], u0[0]), silu_mul(g0[1], u0[1])); w.y = cvt_pk_bf16(silu_mul(g0[2], u0[2]), silu_mul(g0[3], u0[3]));
;                 w.z = cvt_pk_bf16(silu_mul(g1[0], u1[0]), silu_mul(g1[1], u1[1])); w.w = cvt_pk_bf16(silu_mul(g1[2], u1[2]), silu_mul(g1[3], u1[3]));
;                 *(u32x4*)rowp = w; }
	v_cvt_pk_bf16_f32 v100, v100, v101
	v_mul_f32_e32 v101, 0xbfb8aa3b, v108
	v_exp_f32_e32 v101, v101
	v_mul_f32_e32 v102, 0xbfb8aa3b, v109
	v_exp_f32_e32 v102, v102
	v_pk_mul_f32 v[42:43], v[42:43], v[144:145] op_sel:[0,1]
	v_add_f32_e32 v101, 1.0, v101
	v_rcp_f32_e32 v101, v101
	v_add_f32_e32 v102, 1.0, v102
	v_rcp_f32_e32 v102, v102
	v_pk_mul_f32 v[44:45], v[44:45], v[144:145] op_sel:[0,1]
	v_mul_f32_e32 v101, v108, v101
	v_mul_f32_e32 v101, v116, v101
	v_mul_f32_e32 v102, v109, v102
	v_mul_f32_e32 v102, v117, v102
	v_cvt_pk_bf16_f32 v101, v101, v102
	global_store_dwordx4 v[114:115], v[98:101], off nt
	v_pk_mul_f32 v[30:31], v[30:31], v[154:155] op_sel_hi:[1,0]
	v_pk_mul_f32 v[22:23], v[22:23], v[154:155] op_sel_hi:[1,0]
	v_pk_mul_f32 v[100:101], v[84:85], v[148:149] op_sel_hi:[1,0]
	v_pk_mul_f32 v[84:85], v[82:83], v[148:149] op_sel_hi:[1,0]
	v_mul_f32_e32 v82, 0xbfb8aa3b, v94
	v_mul_f32_e32 v83, 0xbfb8aa3b, v95
	v_exp_f32_e32 v82, v82
	v_exp_f32_e32 v83, v83
	v_or_b32_e32 v98, 32, v156
	v_mad_i64_i32 v[98:99], s[2:3], v98, s15, v[158:159]
	v_add_f32_e32 v82, 1.0, v82
	v_add_f32_e32 v83, 1.0, v83
	v_rcp_f32_e32 v82, v82
	v_rcp_f32_e32 v83, v83
	v_lshl_add_u64 v[98:99], v[98:99], 0, v[160:161]
	v_pk_mul_f32 v[32:33], v[32:33], v[154:155] op_sel_hi:[1,0]
	v_mul_f32_e32 v82, v94, v82
	v_mul_f32_e32 v83, v95, v83
	v_mul_f32_e32 v82, v86, v82
	v_mul_f32_e32 v83, v87, v83
	v_cvt_pk_bf16_f32 v82, v82, v83
	v_mul_f32_e32 v83, 0xbfb8aa3b, v96
	v_mul_f32_e32 v86, 0xbfb8aa3b, v97
	v_exp_f32_e32 v83, v83
	v_exp_f32_e32 v86, v86
	v_pk_mul_f32 v[24:25], v[24:25], v[154:155] op_sel_hi:[1,0]
	v_pk_mul_f32 v[26:27], v[26:27], v[154:155] op_sel_hi:[1,0]
	v_add_f32_e32 v83, 1.0, v83
	v_add_f32_e32 v86, 1.0, v86
	v_rcp_f32_e32 v83, v83
	v_rcp_f32_e32 v86, v86
	v_pk_mul_f32 v[28:29], v[28:29], v[154:155] op_sel_hi:[1,0]
	v_pk_mul_f32 v[14:15], v[14:15], v[142:143] op_sel_hi:[1,0]
	v_mul_f32_e32 v83, v96, v83
	v_mul_f32_e32 v86, v97, v86
	v_mul_f32_e32 v83, v88, v83
	v_mul_f32_e32 v86, v89, v86
	v_cvt_pk_bf16_f32 v83, v83, v86
	v_mul_f32_e32 v86, 0xbfb8aa3b, v90
	v_exp_f32_e32 v86, v86
	v_pk_mul_f32 v[6:7], v[6:7], v[142:143] op_sel_hi:[1,0]
	v_pk_mul_f32 v[16:17], v[16:17], v[142:143] op_sel_hi:[1,0]
	v_pk_mul_f32 v[8:9], v[8:9], v[142:143] op_sel_hi:[1,0]
	v_add_f32_e32 v86, 1.0, v86
	v_rcp_f32_e32 v86, v86
	v_pk_mul_f32 v[10:11], v[10:11], v[142:143] op_sel_hi:[1,0]
	v_pk_mul_f32 v[12:13], v[12:13], v[142:143] op_sel_hi:[1,0]
	s_mov_b64 s[20:21], -1
	v_mul_f32_e32 v86, v90, v86
	v_mul_f32_e32 v84, v84, v86
	v_mul_f32_e32 v86, 0xbfb8aa3b, v91
	v_exp_f32_e32 v86, v86
	s_andn2_b64 vcc, exec, s[6:7]
	v_add_f32_e32 v86, 1.0, v86
	v_rcp_f32_e32 v86, v86
	s_nop 0
	v_mul_f32_e32 v86, v91, v86
	v_mul_f32_e32 v85, v85, v86
	v_cvt_pk_bf16_f32 v84, v84, v85
	v_mul_f32_e32 v85, 0xbfb8aa3b, v92
	v_exp_f32_e32 v85, v85
	v_mul_f32_e32 v86, 0xbfb8aa3b, v93
	v_exp_f32_e32 v86, v86
	v_add_f32_e32 v85, 1.0, v85
	v_rcp_f32_e32 v85, v85
	v_add_f32_e32 v86, 1.0, v86
	v_rcp_f32_e32 v86, v86
	v_mul_f32_e32 v85, v92, v85
	v_mul_f32_e32 v85, v100, v85
	v_mul_f32_e32 v86, v93, v86
	v_mul_f32_e32 v86, v101, v86
	v_cvt_pk_bf16_f32 v85, v85, v86
	global_store_dwordx4 v[98:99], v[82:85], off nt
	s_nop 1
	v_pk_mul_f32 v[84:85], v[68:69], v[152:153] op_sel_hi:[1,0]
	v_pk_mul_f32 v[68:69], v[66:67], v[152:153] op_sel_hi:[1,0]
	v_mul_f32_e32 v66, 0xbfb8aa3b, v78
	v_mul_f32_e32 v67, 0xbfb8aa3b, v79
	v_exp_f32_e32 v66, v66
	v_exp_f32_e32 v67, v67
	v_or_b32_e32 v82, 48, v156
	v_mad_i64_i32 v[82:83], s[2:3], v82, s15, v[158:159]
	v_add_f32_e32 v66, 1.0, v66
	v_add_f32_e32 v67, 1.0, v67
	v_rcp_f32_e32 v66, v66
	v_rcp_f32_e32 v67, v67
	v_lshl_add_u64 v[82:83], v[82:83], 0, v[160:161]
	v_mul_f32_e32 v66, v78, v66
	v_mul_f32_e32 v67, v79, v67
	v_mul_f32_e32 v66, v70, v66
	v_mul_f32_e32 v67, v71, v67
	v_cvt_pk_bf16_f32 v66, v66, v67
	v_mul_f32_e32 v67, 0xbfb8aa3b, v80
	v_mul_f32_e32 v70, 0xbfb8aa3b, v81
	v_exp_f32_e32 v67, v67
	v_exp_f32_e32 v70, v70
	v_add_f32_e32 v67, 1.0, v67
	v_add_f32_e32 v70, 1.0, v70
	v_rcp_f32_e32 v67, v67
	v_rcp_f32_e32 v70, v70
	v_mul_f32_e32 v67, v80, v67
	v_mul_f32_e32 v70, v81, v70
	v_mul_f32_e32 v67, v72, v67
	v_mul_f32_e32 v70, v73, v70
	v_cvt_pk_bf16_f32 v67, v67, v70
	v_mul_f32_e32 v70, 0xbfb8aa3b, v74
	v_exp_f32_e32 v70, v70
	s_nop 0
	v_add_f32_e32 v70, 1.0, v70
	v_rcp_f32_e32 v70, v70
	s_nop 0
	v_mul_f32_e32 v70, v74, v70
	v_mul_f32_e32 v68, v68, v70
	v_mul_f32_e32 v70, 0xbfb8aa3b, v75
	v_exp_f32_e32 v70, v70
	s_nop 0
	v_add_f32_e32 v70, 1.0, v70
	v_rcp_f32_e32 v70, v70
	s_nop 0
	v_mul_f32_e32 v70, v75, v70
	v_mul_f32_e32 v69, v69, v70
	v_cvt_pk_bf16_f32 v68, v68, v69
	v_mul_f32_e32 v69, 0xbfb8aa3b, v76
	v_exp_f32_e32 v69, v69
	v_mul_f32_e32 v70, 0xbfb8aa3b, v77
	v_exp_f32_e32 v70, v70
	v_add_f32_e32 v69, 1.0, v69
	v_rcp_f32_e32 v69, v69
	v_add_f32_e32 v70, 1.0, v70
	v_rcp_f32_e32 v70, v70
	v_mul_f32_e32 v69, v76, v69
	v_mul_f32_e32 v69, v84, v69
	v_mul_f32_e32 v70, v77, v70
	v_mul_f32_e32 v70, v85, v70
	v_cvt_pk_bf16_f32 v69, v69, v70
	global_store_dwordx4 v[82:83], v[66:69], off nt
	s_nop 1
	v_pk_mul_f32 v[68:69], v[52:53], v[144:145] op_sel_hi:[1,0]
	v_pk_mul_f32 v[52:53], v[50:51], v[144:145] op_sel_hi:[1,0]
	v_mul_f32_e32 v50, 0xbfb8aa3b, v62
	v_mul_f32_e32 v51, 0xbfb8aa3b, v63
	v_exp_f32_e32 v50, v50
	v_exp_f32_e32 v51, v51
	v_add_u32_e32 v66, 0x80, v156
	v_mad_i64_i32 v[66:67], s[2:3], v66, s15, v[158:159]
	v_add_f32_e32 v50, 1.0, v50
	v_add_f32_e32 v51, 1.0, v51
	v_rcp_f32_e32 v50, v50
	v_rcp_f32_e32 v51, v51
	v_lshl_add_u64 v[66:67], v[66:67], 0, v[160:161]
	v_mul_f32_e32 v50, v62, v50
	v_mul_f32_e32 v51, v63, v51
	v_mul_f32_e32 v50, v54, v50
; __device__ __forceinline__ unsigned cvt_pk_bf16(float lo, float hi) { unsigned r; asm volatile("v_cvt_pk_bf16_f32 %0, %1, %2" : "=v"(r) : "v"(lo), "v"(hi)); return r; }
; __device__ __forceinline__ float silu_mul(float g, float u) { const float e = __builtin_amdgcn_exp2f(g * -1.4426950408889634f); return g * __builtin_amdgcn_rcpf(1.0f + e) * u; }
;     __device__ __forceinline__ void operator()(const f32x4 (&acc)[2][2][4][2], const Unit& u, int wr, int wc, int fr, int fq, const float (&rsv)[8]) const {
;         const int row0 = u.pm * BM + wr * 64 + fr; const int col0 = u.pn * HALF + wc * 32 + 8 * fq;
; #pragma unroll
;         for (int ai = 0; ai < 2; ++ai)
; #pragma unroll
;             for (int m = 0; m < 4; ++m) { bf16_t* rowp = O + (size_t)(row0 + ai * HALF + m * 16) * ldc + col0;
;                 const float sc = rsv[4 * ai + m];
;                 const f32x4 g0 = acc[ai][0][m][0] * sc, g1 = acc[ai][0][m][1] * sc, u0 = acc[ai][1][m][0] * sc, u1 = acc[ai][1][m][1] * sc;
;                 u32x4 w; w.x = cvt_pk_bf16(silu_mul(g0[0], u0[0]), silu_mul(g0[1], u0[1])); w.y = cvt_pk_bf16(silu_mul(g0[2], u0[2]), silu_mul(g0[3], u0[3]));
;                 w.z = cvt_pk_bf16(silu_mul(g1[0], u1[0]), silu_mul(g1[1], u1[1])); w.w = cvt_pk_bf16(silu_mul(g1[2], u1[2]), silu_mul(g1[3], u1[3]));
;                 *(u32x4*)rowp = w; }
	v_mul_f32_e32 v51, v55, v51
	v_cvt_pk_bf16_f32 v50, v50, v51
	v_mul_f32_e32 v51, 0xbfb8aa3b, v64
	v_mul_f32_e32 v54, 0xbfb8aa3b, v65
	v_exp_f32_e32 v51, v51
	v_exp_f32_e32 v54, v54
	v_add_f32_e32 v51, 1.0, v51
	v_add_f32_e32 v54, 1.0, v54
	v_rcp_f32_e32 v51, v51
	v_rcp_f32_e32 v54, v54
	v_mul_f32_e32 v51, v64, v51
	v_mul_f32_e32 v54, v65, v54
	v_mul_f32_e32 v51, v56, v51
	v_mul_f32_e32 v54, v57, v54
	v_cvt_pk_bf16_f32 v51, v51, v54
	v_mul_f32_e32 v54, 0xbfb8aa3b, v58
	v_exp_f32_e32 v54, v54
	s_nop 0
	v_add_f32_e32 v54, 1.0, v54
	v_rcp_f32_e32 v54, v54
	s_nop 0
	v_mul_f32_e32 v54, v58, v54
	v_mul_f32_e32 v52, v52, v54
	v_mul_f32_e32 v54, 0xbfb8aa3b, v59
	v_exp_f32_e32 v54, v54
	s_nop 0
	v_add_f32_e32 v54, 1.0, v54
	v_rcp_f32_e32 v54, v54
	s_nop 0
	v_mul_f32_e32 v54, v59, v54
	v_mul_f32_e32 v53, v53, v54
	v_cvt_pk_bf16_f32 v52, v52, v53
	v_mul_f32_e32 v53, 0xbfb8aa3b, v60
	v_exp_f32_e32 v53, v53
	v_mul_f32_e32 v54, 0xbfb8aa3b, v61
	v_exp_f32_e32 v54, v54
	v_add_f32_e32 v53, 1.0, v53
	v_rcp_f32_e32 v53, v53
	v_add_f32_e32 v54, 1.0, v54
	v_rcp_f32_e32 v54, v54
	v_mul_f32_e32 v53, v60, v53
	v_mul_f32_e32 v53, v68, v53
	v_mul_f32_e32 v54, v61, v54
	v_mul_f32_e32 v54, v69, v54
	v_cvt_pk_bf16_f32 v53, v53, v54
	global_store_dwordx4 v[66:67], v[50:53], off nt
	s_nop 1
	v_pk_mul_f32 v[52:53], v[36:37], v[144:145] op_sel:[0,1]
	v_pk_mul_f32 v[36:37], v[34:35], v[144:145] op_sel:[0,1]
	v_mul_f32_e32 v34, 0xbfb8aa3b, v46
	v_mul_f32_e32 v35, 0xbfb8aa3b, v47
	v_exp_f32_e32 v34, v34
	v_exp_f32_e32 v35, v35
	v_add_u32_e32 v50, 0x90, v156
	v_mad_i64_i32 v[50:51], s[2:3], v50, s15, v[158:159]
	v_add_f32_e32 v34, 1.0, v34
	v_add_f32_e32 v35, 1.0, v35
	v_rcp_f32_e32 v34, v34
	v_rcp_f32_e32 v35, v35
	v_lshl_add_u64 v[50:51], v[50:51], 0, v[160:161]
	v_mul_f32_e32 v34, v46, v34
	v_mul_f32_e32 v35, v47, v35
	v_mul_f32_e32 v34, v38, v34
	v_mul_f32_e32 v35, v39, v35
	v_cvt_pk_bf16_f32 v34, v34, v35
	v_mul_f32_e32 v35, 0xbfb8aa3b, v48
	v_mul_f32_e32 v38, 0xbfb8aa3b, v49
	v_exp_f32_e32 v35, v35
	v_exp_f32_e32 v38, v38
	v_add_f32_e32 v35, 1.0, v35
	v_add_f32_e32 v38, 1.0, v38
	v_rcp_f32_e32 v35, v35
	v_rcp_f32_e32 v38, v38
	v_mul_f32_e32 v35, v48, v35
	v_mul_f32_e32 v38, v49, v38
	v_mul_f32_e32 v35, v40, v35
	v_mul_f32_e32 v38, v41, v38
	v_cvt_pk_bf16_f32 v35, v35, v38
	v_mul_f32_e32 v38, 0xbfb8aa3b, v42
	v_exp_f32_e32 v38, v38
	s_nop 0
	v_add_f32_e32 v38, 1.0, v38
	v_rcp_f32_e32 v38, v38
	s_nop 0
	v_mul_f32_e32 v38, v42, v38
	v_mul_f32_e32 v36, v36, v38
	v_mul_f32_e32 v38, 0xbfb8aa3b, v43
	v_exp_f32_e32 v38, v38
	s_nop 0
	v_add_f32_e32 v38, 1.0, v38
	v_rcp_f32_e32 v38, v38
	s_nop 0
	v_mul_f32_e32 v38, v43, v38
	v_mul_f32_e32 v37, v37, v38
	v_cvt_pk_bf16_f32 v36, v36, v37
	v_mul_f32_e32 v37, 0xbfb8aa3b, v44
	v_exp_f32_e32 v37, v37
	v_mul_f32_e32 v38, 0xbfb8aa3b, v45
	v_exp_f32_e32 v38, v38
	v_add_f32_e32 v37, 1.0, v37
	v_rcp_f32_e32 v37, v37
	v_add_f32_e32 v38, 1.0, v38
	v_rcp_f32_e32 v38, v38
	v_mul_f32_e32 v37, v44, v37
	v_mul_f32_e32 v37, v52, v37
	v_mul_f32_e32 v38, v45, v38
	v_mul_f32_e32 v38, v53, v38
	v_cvt_pk_bf16_f32 v37, v37, v38
	global_store_dwordx4 v[50:51], v[34:37], off nt
	s_nop 1
	v_pk_mul_f32 v[36:37], v[20:21], v[154:155] op_sel_hi:[1,0]
	v_pk_mul_f32 v[20:21], v[18:19], v[154:155] op_sel_hi:[1,0]
	v_mul_f32_e32 v18, 0xbfb8aa3b, v30
	v_mul_f32_e32 v19, 0xbfb8aa3b, v31
	v_exp_f32_e32 v18, v18
	v_exp_f32_e32 v19, v19
	v_add_u32_e32 v34, 0xa0, v156
	v_mad_i64_i32 v[34:35], s[2:3], v34, s15, v[158:159]
	v_add_f32_e32 v18, 1.0, v18
	v_add_f32_e32 v19, 1.0, v19
	v_rcp_f32_e32 v18, v18
	v_rcp_f32_e32 v19, v19
	v_lshl_add_u64 v[34:35], v[34:35], 0, v[160:161]
	v_mul_f32_e32 v18, v30, v18
	v_mul_f32_e32 v19, v31, v19
	v_mul_f32_e32 v18, v22, v18
	v_mul_f32_e32 v19, v23, v19
	v_cvt_pk_bf16_f32 v18, v18, v19
	v_mul_f32_e32 v19, 0xbfb8aa3b, v32
	v_mul_f32_e32 v22, 0xbfb8aa3b, v33
	v_exp_f32_e32 v19, v19
	v_exp_f32_e32 v22, v22
	v_add_f32_e32 v19, 1.0, v19
	v_add_f32_e32 v22, 1.0, v22
	v_rcp_f32_e32 v19, v19
	v_rcp_f32_e32 v22, v22
	v_mul_f32_e32 v19, v32, v19
	v_mul_f32_e32 v22, v33, v22
	v_mul_f32_e32 v19, v24, v19
	v_mul_f32_e32 v22, v25, v22
	v_cvt_pk_bf16_f32 v19, v19, v22
	v_mul_f32_e32 v22, 0xbfb8aa3b, v26
	v_exp_f32_e32 v22, v22
	s_nop 0
	v_add_f32_e32 v22, 1.0, v22
	v_rcp_f32_e32 v22, v22
	s_nop 0
	v_mul_f32_e32 v22, v26, v22
	v_mul_f32_e32 v20, v20, v22
	v_mul_f32_e32 v22, 0xbfb8aa3b, v27
	v_exp_f32_e32 v22, v22
	s_nop 0
	v_add_f32_e32 v22, 1.0, v22
	v_rcp_f32_e32 v22, v22
	s_nop 0
	v_mul_f32_e32 v22, v27, v22
	v_mul_f32_e32 v21, v21, v22
	v_cvt_pk_bf16_f32 v20, v20, v21
	v_mul_f32_e32 v21, 0xbfb8aa3b, v28
	v_exp_f32_e32 v21, v21
	v_mul_f32_e32 v22, 0xbfb8aa3b, v29
	v_exp_f32_e32 v22, v22
	v_add_f32_e32 v21, 1.0, v21
	v_rcp_f32_e32 v21, v21
	v_add_f32_e32 v22, 1.0, v22
	v_rcp_f32_e32 v22, v22
	v_mul_f32_e32 v21, v28, v21
	v_mul_f32_e32 v21, v36, v21
	v_mul_f32_e32 v22, v29, v22
	v_mul_f32_e32 v22, v37, v22
	v_cvt_pk_bf16_f32 v21, v21, v22
	global_store_dwordx4 v[34:35], v[18:21], off nt
	s_nop 1
	v_pk_mul_f32 v[20:21], v[4:5], v[142:143] op_sel_hi:[1,0]
	v_pk_mul_f32 v[4:5], v[2:3], v[142:143] op_sel_hi:[1,0]
	v_mul_f32_e32 v2, 0xbfb8aa3b, v14
	v_mul_f32_e32 v3, 0xbfb8aa3b, v15
	v_exp_f32_e32 v2, v2
	v_exp_f32_e32 v3, v3
	v_add_u32_e32 v18, 0xb0, v156
	v_mad_i64_i32 v[18:19], s[2:3], v18, s15, v[158:159]
	v_add_f32_e32 v2, 1.0, v2
	v_add_f32_e32 v3, 1.0, v3
	v_rcp_f32_e32 v2, v2
	v_rcp_f32_e32 v3, v3
	v_lshl_add_u64 v[18:19], v[18:19], 0, v[160:161]
	v_mul_f32_e32 v2, v14, v2
	v_mul_f32_e32 v3, v15, v3
	v_mul_f32_e32 v2, v6, v2
	v_mul_f32_e32 v3, v7, v3
	v_cvt_pk_bf16_f32 v2, v2, v3
	v_mul_f32_e32 v3, 0xbfb8aa3b, v16
	v_mul_f32_e32 v6, 0xbfb8aa3b, v17
	v_exp_f32_e32 v3, v3
	v_exp_f32_e32 v6, v6
	v_add_f32_e32 v3, 1.0, v3
	v_add_f32_e32 v6, 1.0, v6
	v_rcp_f32_e32 v3, v3
	v_rcp_f32_e32 v6, v6
	v_mul_f32_e32 v3, v16, v3
	v_mul_f32_e32 v6, v17, v6
	v_mul_f32_e32 v3, v8, v3
	v_mul_f32_e32 v6, v9, v6
	v_cvt_pk_bf16_f32 v3, v3, v6
	v_mul_f32_e32 v6, 0xbfb8aa3b, v10
	v_exp_f32_e32 v6, v6
	s_nop 0
	v_add_f32_e32 v6, 1.0, v6
	v_rcp_f32_e32 v6, v6
	s_nop 0
	v_mul_f32_e32 v6, v10, v6
	v_mul_f32_e32 v4, v4, v6
	v_mul_f32_e32 v6, 0xbfb8aa3b, v11
	v_exp_f32_e32 v6, v6
	s_nop 0
	v_add_f32_e32 v6, 1.0, v6
	v_rcp_f32_e32 v6, v6
	s_nop 0
	v_mul_f32_e32 v6, v11, v6
	v_mul_f32_e32 v5, v5, v6
	v_cvt_pk_bf16_f32 v4, v4, v5
	v_mul_f32_e32 v5, 0xbfb8aa3b, v12
	v_exp_f32_e32 v5, v5
	v_mul_f32_e32 v6, 0xbfb8aa3b, v13
	v_exp_f32_e32 v6, v6
	v_add_f32_e32 v5, 1.0, v5
	v_rcp_f32_e32 v5, v5
	v_add_f32_e32 v6, 1.0, v6
	v_rcp_f32_e32 v6, v6
	v_mul_f32_e32 v5, v12, v5
	v_mul_f32_e32 v5, v20, v5
	v_mul_f32_e32 v6, v13, v6
	v_mul_f32_e32 v6, v21, v6
	v_cvt_pk_bf16_f32 v5, v5, v6
	global_store_dwordx4 v[18:19], v[2:5], off nt
	s_cbranch_vccnz .LBB0_724
	s_andn2_b64 vcc, exec, s[8:9]
	s_cbranch_vccnz .LBB0_723
	s_barrier
	s_branch .LBB0_723
